# v9: v8 + first two super-phases after each epilogue use vmcnt(24) so the epilogue stores drain behind MFMAs
# speedup vs baseline: 1.0081x; 1.0081x over previous
.LBB0_63:
	s_add_u32 s40, s40, 0x80
	s_addc_u32 s41, s41, 0
	s_add_u32 vcc_lo, s42, 0x100
	v_mov_b32_e32 v0, 0
	s_addc_u32 vcc_hi, s43, 0
	s_mov_b32 s42, 0
	v_mov_b32_e32 v1, v0
	v_mov_b32_e32 v2, v0
	v_mov_b32_e32 v3, v0
	v_mov_b32_e32 v4, v0
	v_mov_b32_e32 v5, v0
	v_mov_b32_e32 v6, v0
	v_mov_b32_e32 v7, v0
	v_mov_b32_e32 v16, v0
	v_mov_b32_e32 v17, v0
	v_mov_b32_e32 v18, v0
	v_mov_b32_e32 v19, v0
	v_mov_b32_e32 v20, v0
	v_mov_b32_e32 v21, v0
	v_mov_b32_e32 v22, v0
	v_mov_b32_e32 v23, v0
	v_mov_b32_e32 v32, v0
	v_mov_b32_e32 v33, v0
	v_mov_b32_e32 v34, v0
	v_mov_b32_e32 v35, v0
	v_mov_b32_e32 v36, v0
	v_mov_b32_e32 v37, v0
	v_mov_b32_e32 v38, v0
	v_mov_b32_e32 v39, v0
	v_mov_b32_e32 v48, v0
	v_mov_b32_e32 v49, v0
	v_mov_b32_e32 v50, v0
	v_mov_b32_e32 v51, v0
	v_mov_b32_e32 v52, v0
	v_mov_b32_e32 v53, v0
	v_mov_b32_e32 v54, v0
	v_mov_b32_e32 v55, v0
	v_mov_b32_e32 v8, v0
	v_mov_b32_e32 v9, v0
	v_mov_b32_e32 v10, v0
	v_mov_b32_e32 v11, v0
	v_mov_b32_e32 v12, v0
	v_mov_b32_e32 v13, v0
	v_mov_b32_e32 v14, v0
	v_mov_b32_e32 v15, v0
	v_mov_b32_e32 v24, v0
	v_mov_b32_e32 v25, v0
	v_mov_b32_e32 v26, v0
	v_mov_b32_e32 v27, v0
	v_mov_b32_e32 v28, v0
	v_mov_b32_e32 v29, v0
	v_mov_b32_e32 v30, v0
	v_mov_b32_e32 v31, v0
	v_mov_b32_e32 v40, v0
	v_mov_b32_e32 v41, v0
	v_mov_b32_e32 v42, v0
	v_mov_b32_e32 v43, v0
	v_mov_b32_e32 v44, v0
	v_mov_b32_e32 v45, v0
	v_mov_b32_e32 v46, v0
	v_mov_b32_e32 v47, v0
	v_mov_b32_e32 v56, v0
	v_mov_b32_e32 v57, v0
	v_mov_b32_e32 v58, v0
	v_mov_b32_e32 v59, v0
	v_mov_b32_e32 v60, v0
	v_mov_b32_e32 v61, v0
	v_mov_b32_e32 v62, v0
	v_mov_b32_e32 v63, v0
	v_mov_b32_e32 v64, v0
	v_mov_b32_e32 v65, v0
	v_mov_b32_e32 v66, v0
	v_mov_b32_e32 v67, v0
	v_mov_b32_e32 v68, v0
	v_mov_b32_e32 v69, v0
	v_mov_b32_e32 v70, v0
	v_mov_b32_e32 v71, v0
	v_mov_b32_e32 v80, v0
	v_mov_b32_e32 v81, v0
	v_mov_b32_e32 v82, v0
	v_mov_b32_e32 v83, v0
	v_mov_b32_e32 v84, v0
	v_mov_b32_e32 v85, v0
	v_mov_b32_e32 v86, v0
	v_mov_b32_e32 v87, v0
	v_mov_b32_e32 v96, v0
	v_mov_b32_e32 v97, v0
	v_mov_b32_e32 v98, v0
	v_mov_b32_e32 v99, v0
	v_mov_b32_e32 v100, v0
	v_mov_b32_e32 v101, v0
	v_mov_b32_e32 v102, v0
	v_mov_b32_e32 v103, v0
	v_mov_b32_e32 v112, v0
	v_mov_b32_e32 v113, v0
	v_mov_b32_e32 v114, v0
	v_mov_b32_e32 v115, v0
	v_mov_b32_e32 v116, v0
	v_mov_b32_e32 v117, v0
	v_mov_b32_e32 v118, v0
	v_mov_b32_e32 v119, v0
	v_mov_b32_e32 v72, v0
	v_mov_b32_e32 v73, v0
	v_mov_b32_e32 v74, v0
	v_mov_b32_e32 v75, v0
	v_mov_b32_e32 v76, v0
	v_mov_b32_e32 v77, v0
	v_mov_b32_e32 v78, v0
	v_mov_b32_e32 v79, v0
	v_mov_b32_e32 v88, v0
	v_mov_b32_e32 v89, v0
	v_mov_b32_e32 v90, v0
	v_mov_b32_e32 v91, v0
	v_mov_b32_e32 v92, v0
	v_mov_b32_e32 v93, v0
	v_mov_b32_e32 v94, v0
	v_mov_b32_e32 v95, v0
	v_mov_b32_e32 v104, v0
	v_mov_b32_e32 v105, v0
	v_mov_b32_e32 v106, v0
	v_mov_b32_e32 v107, v0
	v_mov_b32_e32 v108, v0
	v_mov_b32_e32 v109, v0
	v_mov_b32_e32 v110, v0
	v_mov_b32_e32 v111, v0
	v_mov_b32_e32 v120, v0
	v_mov_b32_e32 v121, v0
	v_mov_b32_e32 v122, v0
	v_mov_b32_e32 v123, v0
	v_mov_b32_e32 v124, v0
	v_mov_b32_e32 v125, v0
	v_mov_b32_e32 v126, v0
	v_mov_b32_e32 v127, v0
	s_cmp_eq_u32 s85, 1
	s_cbranch_scc0 .Lmy_peel

.Lmy_sp3:
	s_add_i32 s5, 0, 0x18000
	s_add_i32 s46, 0, 0x1c000
	v_add_u32_e32 v140, s5, v185
	v_add_u32_e32 v166, s46, v185
	ds_read_b128 v[128:131], v140
	ds_read_b128 v[132:135], v140 offset:1024
	ds_read_b128 v[136:139], v140 offset:2048
	ds_read_b128 v[140:143], v140 offset:3072
	ds_read_b128 v[144:147], v166
	ds_read_b128 v[148:151], v166 offset:1024
	ds_read_b128 v[152:155], v166 offset:2048
	ds_read_b128 v[166:169], v166 offset:3072
	s_add_u32 s42, s42, s30
	s_addc_u32 s43, s43, 0
	s_mov_b32 m0, s72
	v_lshl_add_u64 v[240:241], s[42:43], 0, v[156:157]
	ds_read_b128 v[170:173], v188 offset:32768
	ds_read_b128 v[174:177], v188 offset:33792
	ds_read_b128 v[178:181], v188 offset:34816
	ds_read_b128 v[214:217], v188 offset:35840
	ds_read_b128 v[218:221], v188 offset:36864
	ds_read_b128 v[222:225], v188 offset:37888
	ds_read_b128 v[226:229], v188 offset:38912
	ds_read_b128 v[230:233], v188 offset:39936
	global_load_lds_dwordx4 v[240:241], off
	v_lshl_add_u64 v[240:241], s[42:43], 0, v[158:159]
	s_mov_b32 m0, s76
	s_nop 0
	global_load_lds_dwordx4 v[240:241], off
	s_waitcnt vmcnt(8)
	s_waitcnt lgkmcnt(0)
	s_barrier
	s_setprio 1
	s_waitcnt lgkmcnt(0)
	v_mfma_f32_16x16x32_bf16 v[124:127], v[128:131], v[170:173], v[124:127]
	v_mfma_f32_16x16x32_bf16 v[120:123], v[136:139], v[170:173], v[120:123]
	v_mfma_f32_16x16x32_bf16 v[108:111], v[128:131], v[178:181], v[108:111]
	v_mfma_f32_16x16x32_bf16 v[104:107], v[136:139], v[178:181], v[104:107]
	v_mfma_f32_16x16x32_bf16 v[92:95], v[128:131], v[218:221], v[92:95]
	v_mfma_f32_16x16x32_bf16 v[88:91], v[136:139], v[218:221], v[88:91]
	v_mfma_f32_16x16x32_bf16 v[76:79], v[128:131], v[226:229], v[76:79]
	v_mfma_f32_16x16x32_bf16 v[72:75], v[136:139], v[226:229], v[72:75]
	v_mfma_f32_16x16x32_bf16 v[124:127], v[132:135], v[174:177], v[124:127]
	v_mfma_f32_16x16x32_bf16 v[120:123], v[140:143], v[174:177], v[120:123]
	v_mfma_f32_16x16x32_bf16 v[108:111], v[132:135], v[214:217], v[108:111]
	v_mfma_f32_16x16x32_bf16 v[104:107], v[140:143], v[214:217], v[104:107]
	v_mfma_f32_16x16x32_bf16 v[92:95], v[132:135], v[222:225], v[92:95]
	v_mfma_f32_16x16x32_bf16 v[88:91], v[140:143], v[222:225], v[88:91]
	v_mfma_f32_16x16x32_bf16 v[76:79], v[132:135], v[230:233], v[76:79]
	v_mfma_f32_16x16x32_bf16 v[72:75], v[140:143], v[230:233], v[72:75]
	s_setprio 0
	s_setprio 1
	v_mfma_f32_16x16x32_bf16 v[116:119], v[144:147], v[170:173], v[116:119]
	v_mfma_f32_16x16x32_bf16 v[112:115], v[152:155], v[170:173], v[112:115]
	v_mfma_f32_16x16x32_bf16 v[100:103], v[144:147], v[178:181], v[100:103]
	v_mfma_f32_16x16x32_bf16 v[96:99], v[152:155], v[178:181], v[96:99]
	v_mfma_f32_16x16x32_bf16 v[84:87], v[144:147], v[218:221], v[84:87]
	v_mfma_f32_16x16x32_bf16 v[80:83], v[152:155], v[218:221], v[80:83]
	v_mfma_f32_16x16x32_bf16 v[68:71], v[144:147], v[226:229], v[68:71]
	v_mfma_f32_16x16x32_bf16 v[64:67], v[152:155], v[226:229], v[64:67]
	v_mfma_f32_16x16x32_bf16 v[116:119], v[148:151], v[174:177], v[116:119]
	v_mfma_f32_16x16x32_bf16 v[112:115], v[166:169], v[174:177], v[112:115]
	v_mfma_f32_16x16x32_bf16 v[100:103], v[148:151], v[214:217], v[100:103]
	v_mfma_f32_16x16x32_bf16 v[96:99], v[166:169], v[214:217], v[96:99]
	v_mfma_f32_16x16x32_bf16 v[84:87], v[148:151], v[222:225], v[84:87]
	v_mfma_f32_16x16x32_bf16 v[80:83], v[166:169], v[222:225], v[80:83]
	v_mfma_f32_16x16x32_bf16 v[68:71], v[148:151], v[230:233], v[68:71]
	v_mfma_f32_16x16x32_bf16 v[64:67], v[166:169], v[230:233], v[64:67]
	s_setprio 0
	s_barrier
	s_add_i32 s5, s5, s27
	v_lshl_add_u64 v[182:183], v[182:183], 0, s[70:71]
	s_mov_b32 m0, s5
	ds_read_b128 v[170:173], v188 offset:49152
	ds_read_b128 v[174:177], v188 offset:50176
	ds_read_b128 v[178:181], v188 offset:51200
	ds_read_b128 v[214:217], v188 offset:52224
	ds_read_b128 v[218:221], v188 offset:53248
	ds_read_b128 v[222:225], v188 offset:54272
	ds_read_b128 v[226:229], v188 offset:55296
	ds_read_b128 v[230:233], v188 offset:56320
	global_load_lds_dwordx4 v[182:183], off
	v_lshl_add_u64 v[182:183], v[190:191], 0, s[70:71]
	s_add_i32 m0, s5, 0x2000
	s_add_i32 s5, s46, s27
	global_load_lds_dwordx4 v[182:183], off
	v_lshl_add_u64 v[182:183], v[200:201], 0, s[70:71]
	s_mov_b32 m0, s5
	s_nop 0
	global_load_lds_dwordx4 v[182:183], off
	v_lshl_add_u64 v[182:183], v[234:235], 0, s[70:71]
	s_add_i32 m0, s5, 0x2000
	s_nop 0
	global_load_lds_dwordx4 v[182:183], off
	v_lshl_add_u64 v[182:183], v[236:237], 0, s[70:71]
	s_mov_b32 m0, s81
	s_nop 0
	global_load_lds_dwordx4 v[182:183], off
	v_lshl_add_u64 v[182:183], v[238:239], 0, s[70:71]
	s_mov_b32 m0, s82
	s_nop 0
	global_load_lds_dwordx4 v[182:183], off
	s_waitcnt vmcnt(8)
	s_waitcnt lgkmcnt(0)
	s_barrier
	s_setprio 1
	s_waitcnt lgkmcnt(0)
	v_mfma_f32_16x16x32_bf16 v[60:63], v[128:131], v[170:173], v[60:63]
	v_mfma_f32_16x16x32_bf16 v[56:59], v[136:139], v[170:173], v[56:59]
	v_mfma_f32_16x16x32_bf16 v[44:47], v[128:131], v[178:181], v[44:47]
	v_mfma_f32_16x16x32_bf16 v[40:43], v[136:139], v[178:181], v[40:43]
	v_mfma_f32_16x16x32_bf16 v[28:31], v[128:131], v[218:221], v[28:31]
	v_mfma_f32_16x16x32_bf16 v[24:27], v[136:139], v[218:221], v[24:27]
	v_mfma_f32_16x16x32_bf16 v[12:15], v[128:131], v[226:229], v[12:15]
	v_mfma_f32_16x16x32_bf16 v[8:11], v[136:139], v[226:229], v[8:11]
	v_mfma_f32_16x16x32_bf16 v[60:63], v[132:135], v[174:177], v[60:63]
	v_mfma_f32_16x16x32_bf16 v[56:59], v[140:143], v[174:177], v[56:59]
	v_mfma_f32_16x16x32_bf16 v[44:47], v[132:135], v[214:217], v[44:47]
	v_mfma_f32_16x16x32_bf16 v[40:43], v[140:143], v[214:217], v[40:43]
	v_mfma_f32_16x16x32_bf16 v[28:31], v[132:135], v[222:225], v[28:31]
	v_mfma_f32_16x16x32_bf16 v[24:27], v[140:143], v[222:225], v[24:27]
	v_mfma_f32_16x16x32_bf16 v[12:15], v[132:135], v[230:233], v[12:15]
	v_mfma_f32_16x16x32_bf16 v[8:11], v[140:143], v[230:233], v[8:11]
	s_setprio 0
	s_setprio 1
	v_mfma_f32_16x16x32_bf16 v[52:55], v[144:147], v[170:173], v[52:55]
	v_mfma_f32_16x16x32_bf16 v[48:51], v[152:155], v[170:173], v[48:51]
	v_mfma_f32_16x16x32_bf16 v[36:39], v[144:147], v[178:181], v[36:39]
	v_mfma_f32_16x16x32_bf16 v[32:35], v[152:155], v[178:181], v[32:35]
	v_mfma_f32_16x16x32_bf16 v[20:23], v[144:147], v[218:221], v[20:23]
	v_mfma_f32_16x16x32_bf16 v[16:19], v[152:155], v[218:221], v[16:19]
	v_mfma_f32_16x16x32_bf16 v[4:7], v[144:147], v[226:229], v[4:7]
	v_mfma_f32_16x16x32_bf16 v[0:3], v[152:155], v[226:229], v[0:3]
	v_mfma_f32_16x16x32_bf16 v[52:55], v[148:151], v[174:177], v[52:55]
	v_mfma_f32_16x16x32_bf16 v[48:51], v[166:169], v[174:177], v[48:51]
	v_mfma_f32_16x16x32_bf16 v[36:39], v[148:151], v[214:217], v[36:39]
	v_mfma_f32_16x16x32_bf16 v[32:35], v[166:169], v[214:217], v[32:35]
	v_mfma_f32_16x16x32_bf16 v[20:23], v[148:151], v[222:225], v[20:23]
	v_mfma_f32_16x16x32_bf16 v[16:19], v[166:169], v[222:225], v[16:19]
	v_mfma_f32_16x16x32_bf16 v[4:7], v[148:151], v[230:233], v[4:7]
	v_mfma_f32_16x16x32_bf16 v[0:3], v[166:169], v[230:233], v[0:3]
	s_setprio 0
	s_barrier
	s_add_u32 s40, s40, 0x100
	s_addc_u32 s41, s41, 0
	s_add_u32 vcc_lo, vcc_lo, 0x100
	s_addc_u32 vcc_hi, vcc_hi, 0
	s_cmp_ge_u32 s33, s78
	s_mov_b32 s42, s33
	s_cbranch_scc0 .LBB0_64
	s_and_b64 vcc, exec, s[66:67]
	s_cbranch_vccz .LBB0_67
	s_barrier

.Lmy_peel:
	s_add_i32 s33, s42, 2
	s_add_u32 s46, s40, 0x80
	s_addc_u32 s43, s41, 0
	s_add_i32 s80, 0, 0x10000
	s_cmp_eq_u32 s84, s42
	s_cselect_b32 s43, s1, s43
	s_cselect_b32 s42, s0, s46
	s_cselect_b32 s47, s75, vcc_hi
	s_cselect_b32 s46, s74, vcc_lo
	s_add_i32 s5, 0, 0x14000
	v_add_u32_e32 v140, s80, v185
	v_add_u32_e32 v166, s5, v185
	ds_read_b128 v[128:131], v140
	ds_read_b128 v[132:135], v140 offset:1024
	ds_read_b128 v[136:139], v140 offset:2048
	ds_read_b128 v[140:143], v140 offset:3072
	ds_read_b128 v[144:147], v166
	ds_read_b128 v[148:151], v166 offset:1024
	ds_read_b128 v[152:155], v166 offset:2048
	ds_read_b128 v[166:169], v166 offset:3072
	v_lshl_add_u64 v[182:183], s[40:41], 0, v[162:163]
	s_add_i32 m0, s28, 0xc000
	ds_read_b128 v[170:173], v188
	ds_read_b128 v[174:177], v188 offset:1024
	ds_read_b128 v[178:181], v188 offset:2048
	ds_read_b128 v[214:217], v188 offset:3072
	ds_read_b128 v[218:221], v188 offset:4096
	ds_read_b128 v[222:225], v188 offset:5120
	ds_read_b128 v[226:229], v188 offset:6144
	ds_read_b128 v[230:233], v188 offset:7168
	global_load_lds_dwordx4 v[182:183], off
	v_lshl_add_u64 v[182:183], s[40:41], 0, v[164:165]
	s_add_i32 m0, s28, 0xe000
	s_nop 0
	global_load_lds_dwordx4 v[182:183], off
	s_waitcnt vmcnt(24)
	s_waitcnt lgkmcnt(0)
	s_barrier
	s_setprio 1
	s_waitcnt lgkmcnt(0)
	v_mfma_f32_16x16x32_bf16 v[124:127], v[128:131], v[170:173], v[124:127]
	v_mfma_f32_16x16x32_bf16 v[120:123], v[136:139], v[170:173], v[120:123]
	v_mfma_f32_16x16x32_bf16 v[108:111], v[128:131], v[178:181], v[108:111]
	v_mfma_f32_16x16x32_bf16 v[104:107], v[136:139], v[178:181], v[104:107]
	v_mfma_f32_16x16x32_bf16 v[92:95], v[128:131], v[218:221], v[92:95]
	v_mfma_f32_16x16x32_bf16 v[88:91], v[136:139], v[218:221], v[88:91]
	v_mfma_f32_16x16x32_bf16 v[76:79], v[128:131], v[226:229], v[76:79]
	v_mfma_f32_16x16x32_bf16 v[72:75], v[136:139], v[226:229], v[72:75]
	v_mfma_f32_16x16x32_bf16 v[124:127], v[132:135], v[174:177], v[124:127]
	v_mfma_f32_16x16x32_bf16 v[120:123], v[140:143], v[174:177], v[120:123]
	v_mfma_f32_16x16x32_bf16 v[108:111], v[132:135], v[214:217], v[108:111]
	v_mfma_f32_16x16x32_bf16 v[104:107], v[140:143], v[214:217], v[104:107]
	v_mfma_f32_16x16x32_bf16 v[92:95], v[132:135], v[222:225], v[92:95]
	v_mfma_f32_16x16x32_bf16 v[88:91], v[140:143], v[222:225], v[88:91]
	v_mfma_f32_16x16x32_bf16 v[76:79], v[132:135], v[230:233], v[76:79]
	v_mfma_f32_16x16x32_bf16 v[72:75], v[140:143], v[230:233], v[72:75]
	s_setprio 0
	s_setprio 1
	v_mfma_f32_16x16x32_bf16 v[116:119], v[144:147], v[170:173], v[116:119]
	v_mfma_f32_16x16x32_bf16 v[112:115], v[152:155], v[170:173], v[112:115]
	v_mfma_f32_16x16x32_bf16 v[100:103], v[144:147], v[178:181], v[100:103]
	v_mfma_f32_16x16x32_bf16 v[96:99], v[152:155], v[178:181], v[96:99]
	v_mfma_f32_16x16x32_bf16 v[84:87], v[144:147], v[218:221], v[84:87]
	v_mfma_f32_16x16x32_bf16 v[80:83], v[152:155], v[218:221], v[80:83]
	v_mfma_f32_16x16x32_bf16 v[68:71], v[144:147], v[226:229], v[68:71]
	v_mfma_f32_16x16x32_bf16 v[64:67], v[152:155], v[226:229], v[64:67]
	v_mfma_f32_16x16x32_bf16 v[116:119], v[148:151], v[174:177], v[116:119]
	v_mfma_f32_16x16x32_bf16 v[112:115], v[166:169], v[174:177], v[112:115]
	v_mfma_f32_16x16x32_bf16 v[100:103], v[148:151], v[214:217], v[100:103]
	v_mfma_f32_16x16x32_bf16 v[96:99], v[166:169], v[214:217], v[96:99]
	v_mfma_f32_16x16x32_bf16 v[84:87], v[148:151], v[222:225], v[84:87]
	v_mfma_f32_16x16x32_bf16 v[80:83], v[166:169], v[222:225], v[80:83]
	v_mfma_f32_16x16x32_bf16 v[68:71], v[148:151], v[230:233], v[68:71]
	v_mfma_f32_16x16x32_bf16 v[64:67], v[166:169], v[230:233], v[64:67]
	s_setprio 0
	s_barrier
	s_add_i32 s80, s80, s27
	v_lshl_add_u64 v[182:183], s[46:47], 0, v[192:193]
	s_mov_b32 m0, s80
	ds_read_b128 v[170:173], v188 offset:16384
	ds_read_b128 v[174:177], v188 offset:17408
	ds_read_b128 v[178:181], v188 offset:18432
	ds_read_b128 v[214:217], v188 offset:19456
	ds_read_b128 v[218:221], v188 offset:20480
	ds_read_b128 v[222:225], v188 offset:21504
	ds_read_b128 v[226:229], v188 offset:22528
	ds_read_b128 v[230:233], v188 offset:23552
	global_load_lds_dwordx4 v[182:183], off
	s_add_i32 m0, s80, 0x2000
	v_lshl_add_u64 v[190:191], s[46:47], 0, v[160:161]
	s_add_u32 s46, s46, s30
	s_addc_u32 s47, s47, 0
	s_add_i32 s5, s5, s27
	global_load_lds_dwordx4 v[190:191], off
	v_lshl_add_u64 v[200:201], s[46:47], 0, v[192:193]
	s_mov_b32 m0, s5
	v_lshl_add_u64 v[234:235], s[46:47], 0, v[160:161]
	global_load_lds_dwordx4 v[200:201], off
	s_add_i32 m0, s5, 0x2000
	v_lshl_add_u64 v[236:237], s[42:43], 0, v[156:157]
	global_load_lds_dwordx4 v[234:235], off
	s_mov_b32 m0, s28
	v_lshl_add_u64 v[238:239], s[42:43], 0, v[158:159]
	global_load_lds_dwordx4 v[236:237], off
	s_mov_b32 m0, s69
	s_nop 0
	global_load_lds_dwordx4 v[238:239], off
	s_waitcnt vmcnt(24)
	s_waitcnt lgkmcnt(0)
	s_barrier
	s_setprio 1
	s_waitcnt lgkmcnt(0)
	v_mfma_f32_16x16x32_bf16 v[60:63], v[128:131], v[170:173], v[60:63]
	v_mfma_f32_16x16x32_bf16 v[56:59], v[136:139], v[170:173], v[56:59]
	v_mfma_f32_16x16x32_bf16 v[44:47], v[128:131], v[178:181], v[44:47]
	v_mfma_f32_16x16x32_bf16 v[40:43], v[136:139], v[178:181], v[40:43]
	v_mfma_f32_16x16x32_bf16 v[28:31], v[128:131], v[218:221], v[28:31]
	v_mfma_f32_16x16x32_bf16 v[24:27], v[136:139], v[218:221], v[24:27]
	v_mfma_f32_16x16x32_bf16 v[12:15], v[128:131], v[226:229], v[12:15]
	v_mfma_f32_16x16x32_bf16 v[8:11], v[136:139], v[226:229], v[8:11]
	v_mfma_f32_16x16x32_bf16 v[60:63], v[132:135], v[174:177], v[60:63]
	v_mfma_f32_16x16x32_bf16 v[56:59], v[140:143], v[174:177], v[56:59]
	v_mfma_f32_16x16x32_bf16 v[44:47], v[132:135], v[214:217], v[44:47]
	v_mfma_f32_16x16x32_bf16 v[40:43], v[140:143], v[214:217], v[40:43]
	v_mfma_f32_16x16x32_bf16 v[28:31], v[132:135], v[222:225], v[28:31]
	v_mfma_f32_16x16x32_bf16 v[24:27], v[140:143], v[222:225], v[24:27]
	v_mfma_f32_16x16x32_bf16 v[12:15], v[132:135], v[230:233], v[12:15]
	v_mfma_f32_16x16x32_bf16 v[8:11], v[140:143], v[230:233], v[8:11]
	s_setprio 0
	s_setprio 1
	v_mfma_f32_16x16x32_bf16 v[52:55], v[144:147], v[170:173], v[52:55]
	v_mfma_f32_16x16x32_bf16 v[48:51], v[152:155], v[170:173], v[48:51]
	v_mfma_f32_16x16x32_bf16 v[36:39], v[144:147], v[178:181], v[36:39]
	v_mfma_f32_16x16x32_bf16 v[32:35], v[152:155], v[178:181], v[32:35]
	v_mfma_f32_16x16x32_bf16 v[20:23], v[144:147], v[218:221], v[20:23]
	v_mfma_f32_16x16x32_bf16 v[16:19], v[152:155], v[218:221], v[16:19]
	v_mfma_f32_16x16x32_bf16 v[4:7], v[144:147], v[226:229], v[4:7]
	v_mfma_f32_16x16x32_bf16 v[0:3], v[152:155], v[226:229], v[0:3]
	v_mfma_f32_16x16x32_bf16 v[52:55], v[148:151], v[174:177], v[52:55]
	v_mfma_f32_16x16x32_bf16 v[48:51], v[166:169], v[174:177], v[48:51]
	v_mfma_f32_16x16x32_bf16 v[36:39], v[148:151], v[214:217], v[36:39]
	v_mfma_f32_16x16x32_bf16 v[32:35], v[166:169], v[214:217], v[32:35]
	v_mfma_f32_16x16x32_bf16 v[20:23], v[148:151], v[222:225], v[20:23]
	v_mfma_f32_16x16x32_bf16 v[16:19], v[166:169], v[222:225], v[16:19]
	v_mfma_f32_16x16x32_bf16 v[4:7], v[148:151], v[230:233], v[4:7]
	v_mfma_f32_16x16x32_bf16 v[0:3], v[166:169], v[230:233], v[0:3]
	s_setprio 0
	s_barrier
	s_branch .Lmy_sp3
